# v17 + EpiRes epilogues (w_out, ff2): second half's 8 residual loads issued together with the first half's into registers dead in the epilogue (one exposed memory latency less per tile)
# baseline (speedup 1.0000x reference)
; __device__ __forceinline__ float shx(float v, int lane, int o) { return __int_as_float(__builtin_amdgcn_ds_bpermute((lane ^ o) << 2, __float_as_int(v))); }
; __device__ __forceinline__ u32x4 pack8(const f32x4 a, const f32x4 b) { u32x4 w; w.x = cvt_pk_bf16(a[0], a[1]); w.y = cvt_pk_bf16(a[2], a[3]); w.z = cvt_pk_bf16(b[0], b[1]); w.w = cvt_pk_bf16(b[2], b[3]); return w; }
; __device__ __forceinline__ void unpack8(const u32x4 w, f32x4& a, f32x4& b) { a = (f32x4){bflo(w.x), bfhi(w.x), bflo(w.y), bfhi(w.y)}; b = (f32x4){bflo(w.z), bfhi(w.z), bflo(w.w), bfhi(w.w)}; }
;     __device__ __forceinline__ void operator()(const Acc& acc, const Unit& u, int wr, int wc, int fr, int fq) const {
;     ...
;         for (int ai = 0; ai < 2; ++ai) {
;             u32x4 hv[4][2];
; #pragma unroll
;             for (int m = 0; m < 4; ++m)
; #pragma unroll
;                 for (int bj = 0; bj < 2; ++bj) hv[m][bj] = *(const u32x4*)(hb + (size_t)(row0 + ai * 128 + m * 16) * DM + col0 + bj * 128);
; #pragma unroll
;             for (int m = 0; m < 4; ++m) { const size_t row = (size_t)(row0 + ai * 128 + m * 16); float sq = 0.f;
; #pragma unroll
;                 for (int bj = 0; bj < 2; ++bj) { f32x4 o0, o1; unpack8(hv[m][bj], o0, o1); o0 += acc[ai][bj][m][0] * sc; o1 += acc[ai][bj][m][1] * sc;
;                     *(u32x4*)(hb + row * DM + col0 + bj * 128) = pack8(o0, o1);
;                     sq += ((o0[0] * o0[0] + o0[1] * o0[1]) + (o0[2] * o0[2] + o0[3] * o0[3])) + ((o1[0] * o1[0] + o1[1] * o1[1]) + (o1[2] * o1[2] + o1[3] * o1[3])); }
;                 const int lane = fq * 16 + fr; sq += shx(sq, lane, 16); sq += shx(sq, lane, 32);
;                 if (fq == 0) ssq[row * 16 + u.pn * 4 + wc] = sq; } }
.LBB0_66:
.LBB0_67:
	v_lshl_add_u32 v172, s30, 8, v130
	v_lshlrev_b32_e32 v130, 2, v133
	v_lshlrev_b64 v[202:203], 1, v[168:169]
	v_ashrrev_i32_e32 v173, 31, v172
	v_lshl_add_u32 v130, v132, 6, v130
	v_lshl_add_u64 v[170:171], s[36:37], 0, v[202:203]
	v_lshlrev_b64 v[204:205], 11, v[172:173]
	v_xor_b32_e32 v191, 64, v130
	v_xor_b32_e32 v190, 0x80, v130
	v_lshl_add_u64 v[130:131], v[170:171], 0, v[204:205]
	s_mov_b32 s100, 0x40000
	s_mov_b32 s101, 0
	global_load_dwordx4 v[192:195], v[130:131], off
	global_load_dwordx4 v[154:157], v[130:131], off offset:256
	v_lshl_add_u64 v[206:207], v[130:131], 0, s[100:101]
	global_load_dwordx4 v[210:213], v[206:207], off
	global_load_dwordx4 v[214:217], v[206:207], off offset:256
	v_add_u32_e32 v182, 16, v172
	v_ashrrev_i32_e32 v183, 31, v182
	v_add_u32_e32 v178, 32, v172
	v_lshlrev_b64 v[184:185], 11, v[182:183]
	v_ashrrev_i32_e32 v179, 31, v178
	v_add_u32_e32 v174, 48, v172
	v_lshl_add_u64 v[130:131], v[170:171], 0, v[184:185]
	v_lshlrev_b64 v[180:181], 11, v[178:179]
	v_ashrrev_i32_e32 v175, 31, v174
	global_load_dwordx4 v[150:153], v[130:131], off
	global_load_dwordx4 v[146:149], v[130:131], off offset:256
	v_lshl_add_u64 v[206:207], v[130:131], 0, s[100:101]
	global_load_dwordx4 v[218:221], v[206:207], off
	global_load_dwordx4 v[222:225], v[206:207], off offset:256
	v_lshl_add_u64 v[130:131], v[170:171], 0, v[180:181]
	v_lshlrev_b64 v[176:177], 11, v[174:175]
	global_load_dwordx4 v[142:145], v[130:131], off
	global_load_dwordx4 v[138:141], v[130:131], off offset:256
	v_lshl_add_u64 v[206:207], v[130:131], 0, s[100:101]
	global_load_dwordx4 v[240:243], v[206:207], off
	global_load_dwordx4 v[244:247], v[206:207], off offset:256
	v_lshl_add_u64 v[130:131], v[170:171], 0, v[176:177]
	v_cmp_eq_u32_e32 vcc, 0, v132
	v_lshl_add_u64 v[206:207], v[130:131], 0, s[100:101]
	global_load_dwordx4 v[248:251], v[206:207], off
	global_load_dwordx2 v[226:227], v[206:207], off offset:256
	global_load_dword v239, v[206:207], off offset:264
	global_load_dword v159, v[206:207], off offset:268
	global_load_dwordx4 v[134:137], v[130:131], off
	s_nop 0
	global_load_dwordx4 v[130:133], v[130:131], off offset:256
	v_lshl_add_u64 v[204:205], s[36:37], 0, v[204:205]
	v_lshl_add_u64 v[202:203], v[204:205], 0, v[202:203]
	s_waitcnt vmcnt(0)
	v_lshlrev_b32_e32 v206, 16, v192
	v_and_b32_e32 v207, 0xffff0000, v192
	v_lshlrev_b32_e32 v192, 16, v193
	v_and_b32_e32 v193, 0xffff0000, v193
	v_lshlrev_b32_e32 v208, 16, v194
	v_and_b32_e32 v209, 0xffff0000, v194
	v_lshlrev_b32_e32 v194, 16, v195
	v_and_b32_e32 v195, 0xffff0000, v195
	v_pk_add_f32 v[128:129], v[128:129], v[192:193]
	v_pk_add_f32 v[126:127], v[126:127], v[206:207]
	v_pk_add_f32 v[192:193], v[124:125], v[194:195]
	v_pk_add_f32 v[194:195], v[122:123], v[208:209]
	v_cvt_pk_bf16_f32 v122, v126, v127
	v_cvt_pk_bf16_f32 v123, v128, v129
	v_cvt_pk_bf16_f32 v124, v194, v195
	v_cvt_pk_bf16_f32 v125, v192, v193
	global_store_dwordx4 v[202:203], v[122:125], off
	s_nop 1
	v_mul_f32_e32 v122, v127, v127
	v_mul_f32_e32 v123, v129, v129
	v_fmac_f32_e32 v122, v126, v126
	v_fmac_f32_e32 v123, v128, v128
	v_add_f32_e32 v122, v122, v123
	v_mul_f32_e32 v123, v195, v195
	v_mul_f32_e32 v124, v193, v193
	v_fmac_f32_e32 v123, v194, v194
	v_fmac_f32_e32 v124, v192, v192
	v_add_f32_e32 v123, v123, v124
	v_add_f32_e32 v192, v122, v123
	v_lshlrev_b32_e32 v122, 16, v154
	v_and_b32_e32 v123, 0xffff0000, v154
	v_lshlrev_b32_e32 v124, 16, v155
	v_and_b32_e32 v125, 0xffff0000, v155
	v_lshlrev_b32_e32 v126, 16, v156
	v_and_b32_e32 v127, 0xffff0000, v156
	v_lshlrev_b32_e32 v128, 16, v157
	v_and_b32_e32 v129, 0xffff0000, v157
	v_pk_add_f32 v[120:121], v[120:121], v[124:125]
	v_pk_add_f32 v[118:119], v[118:119], v[122:123]
	v_pk_add_f32 v[122:123], v[116:117], v[128:129]
	v_pk_add_f32 v[124:125], v[114:115], v[126:127]
	v_cvt_pk_bf16_f32 v114, v118, v119
	v_cvt_pk_bf16_f32 v115, v120, v121
	v_cvt_pk_bf16_f32 v116, v124, v125
	v_cvt_pk_bf16_f32 v117, v122, v123
	global_store_dwordx4 v[202:203], v[114:117], off offset:256
	s_nop 1
	v_mul_f32_e32 v114, v119, v119
	v_mul_f32_e32 v115, v121, v121
	v_fmac_f32_e32 v114, v118, v118
	v_fmac_f32_e32 v115, v120, v120
	v_add_f32_e32 v114, v114, v115
	v_mul_f32_e32 v115, v125, v125
	v_mul_f32_e32 v116, v123, v123
	v_fmac_f32_e32 v115, v124, v124
	v_fmac_f32_e32 v116, v122, v122
	v_add_f32_e32 v115, v115, v116
	v_add_f32_e32 v114, v114, v115
	v_add_f32_e32 v114, v192, v114
	ds_bpermute_b32 v115, v191, v114
	s_waitcnt lgkmcnt(0)
	v_add_f32_e32 v114, v114, v115
	ds_bpermute_b32 v115, v190, v114
	s_and_saveexec_b64 s[60:61], vcc
	s_cbranch_execz .LBB0_69
	s_waitcnt lgkmcnt(0)
	v_add_f32_e32 v116, v114, v115
	s_lshl_b32 s22, s46, 2
	v_lshlrev_b64 v[114:115], 6, v[172:173]
	s_ashr_i32 s23, s22, 31
	v_lshl_add_u64 v[114:115], s[84:85], 0, v[114:115]
	v_lshl_add_u64 v[114:115], s[22:23], 2, v[114:115]
	s_lshl_b32 s86, s74, 2
	v_lshl_add_u64 v[114:115], v[114:115], 0, s[86:87]
	global_store_dword v[114:115], v116, off

; __device__ __forceinline__ float shx(float v, int lane, int o) { return __int_as_float(__builtin_amdgcn_ds_bpermute((lane ^ o) << 2, __float_as_int(v))); }
; __device__ __forceinline__ u32x4 pack8(const f32x4 a, const f32x4 b) { u32x4 w; w.x = cvt_pk_bf16(a[0], a[1]); w.y = cvt_pk_bf16(a[2], a[3]); w.z = cvt_pk_bf16(b[0], b[1]); w.w = cvt_pk_bf16(b[2], b[3]); return w; }
; __device__ __forceinline__ void unpack8(const u32x4 w, f32x4& a, f32x4& b) { a = (f32x4){bflo(w.x), bfhi(w.x), bflo(w.y), bfhi(w.y)}; b = (f32x4){bflo(w.z), bfhi(w.z), bflo(w.w), bfhi(w.w)}; }
;     __device__ __forceinline__ void operator()(const Acc& acc, const Unit& u, int wr, int wc, int fr, int fq) const {
;     ...
;             for (int m = 0; m < 4; ++m)
; #pragma unroll
;                 for (int bj = 0; bj < 2; ++bj) hv[m][bj] = *(const u32x4*)(hb + (size_t)(row0 + ai * 128 + m * 16) * DM + col0 + bj * 128);
; #pragma unroll
;             for (int m = 0; m < 4; ++m) { const size_t row = (size_t)(row0 + ai * 128 + m * 16); float sq = 0.f;
; #pragma unroll
;                 for (int bj = 0; bj < 2; ++bj) { f32x4 o0, o1; unpack8(hv[m][bj], o0, o1); o0 += acc[ai][bj][m][0] * sc; o1 += acc[ai][bj][m][1] * sc;
;                     *(u32x4*)(hb + row * DM + col0 + bj * 128) = pack8(o0, o1);
;                     sq += ((o0[0] * o0[0] + o0[1] * o0[1]) + (o0[2] * o0[2] + o0[3] * o0[3])) + ((o1[0] * o1[0] + o1[1] * o1[1]) + (o1[2] * o1[2] + o1[3] * o1[3])); }
;                 const int lane = fq * 16 + fr; sq += shx(sq, lane, 16); sq += shx(sq, lane, 32);
;                 if (fq == 0) ssq[row * 16 + u.pn * 4 + wc] = sq; } }
.LBB0_75:
	s_or_b64 exec, exec, s[60:61]
	v_add_u32_e32 v102, 0x80, v172
	v_ashrrev_i32_e32 v103, 31, v102
	v_lshlrev_b64 v[112:113], 11, v[102:103]
	s_waitcnt lgkmcnt(0)
	v_lshl_add_u64 v[66:67], v[170:171], 0, v[112:113]
	v_add_u32_e32 v98, 0x90, v172
	v_ashrrev_i32_e32 v99, 31, v98
	v_add_u32_e32 v94, 0xa0, v172
	v_lshlrev_b64 v[100:101], 11, v[98:99]
	v_ashrrev_i32_e32 v95, 31, v94
	v_add_u32_e32 v90, 0xb0, v172
	v_lshl_add_u64 v[66:67], v[170:171], 0, v[100:101]
	v_lshlrev_b64 v[96:97], 11, v[94:95]
	v_ashrrev_i32_e32 v91, 31, v90
	v_lshl_add_u64 v[66:67], v[170:171], 0, v[96:97]
	v_lshlrev_b64 v[92:93], 11, v[90:91]
	v_lshl_add_u64 v[66:67], v[170:171], 0, v[92:93]
	s_nop 0
	v_lshl_add_u64 v[112:113], s[36:37], 0, v[112:113]
	v_lshl_add_u64 v[112:113], v[168:169], 1, v[112:113]
	s_waitcnt vmcnt(7)
	v_lshlrev_b32_e32 v114, 16, v210
	v_and_b32_e32 v115, 0xffff0000, v210
	v_lshlrev_b32_e32 v104, 16, v211
	v_and_b32_e32 v105, 0xffff0000, v211
	v_lshlrev_b32_e32 v116, 16, v212
	v_and_b32_e32 v117, 0xffff0000, v212
	v_lshlrev_b32_e32 v106, 16, v213
	v_and_b32_e32 v107, 0xffff0000, v213
	v_pk_add_f32 v[64:65], v[64:65], v[104:105]
	v_pk_add_f32 v[62:63], v[62:63], v[114:115]
	v_pk_add_f32 v[104:105], v[60:61], v[106:107]
	v_pk_add_f32 v[106:107], v[58:59], v[116:117]
	v_cvt_pk_bf16_f32 v58, v62, v63
	v_cvt_pk_bf16_f32 v59, v64, v65
	v_cvt_pk_bf16_f32 v60, v106, v107
	v_cvt_pk_bf16_f32 v61, v104, v105
	global_store_dwordx4 v[112:113], v[58:61], off
	s_nop 1
	v_mul_f32_e32 v58, v63, v63
	v_mul_f32_e32 v59, v65, v65
	v_fmac_f32_e32 v58, v62, v62
	v_fmac_f32_e32 v59, v64, v64
	v_add_f32_e32 v58, v58, v59
	v_mul_f32_e32 v59, v107, v107
	v_mul_f32_e32 v60, v105, v105
	v_fmac_f32_e32 v59, v106, v106
	v_fmac_f32_e32 v60, v104, v104
	v_add_f32_e32 v59, v59, v60
	v_add_f32_e32 v104, v58, v59
	s_waitcnt vmcnt(7)
	v_lshlrev_b32_e32 v58, 16, v214
	v_and_b32_e32 v59, 0xffff0000, v214
	v_lshlrev_b32_e32 v60, 16, v215
	v_and_b32_e32 v61, 0xffff0000, v215
	v_lshlrev_b32_e32 v62, 16, v216
	v_and_b32_e32 v63, 0xffff0000, v216
	v_lshlrev_b32_e32 v64, 16, v217
	v_and_b32_e32 v65, 0xffff0000, v217
	v_pk_add_f32 v[56:57], v[56:57], v[60:61]
	v_pk_add_f32 v[54:55], v[54:55], v[58:59]
	v_pk_add_f32 v[58:59], v[52:53], v[64:65]
	v_pk_add_f32 v[60:61], v[50:51], v[62:63]
	v_cvt_pk_bf16_f32 v50, v54, v55
	v_cvt_pk_bf16_f32 v51, v56, v57
	v_cvt_pk_bf16_f32 v52, v60, v61
	v_cvt_pk_bf16_f32 v53, v58, v59
	global_store_dwordx4 v[112:113], v[50:53], off offset:256
	s_nop 1
	v_mul_f32_e32 v50, v55, v55
	v_mul_f32_e32 v51, v57, v57
	v_fmac_f32_e32 v50, v54, v54
	v_fmac_f32_e32 v51, v56, v56
	v_add_f32_e32 v50, v50, v51
	v_mul_f32_e32 v51, v61, v61
	v_mul_f32_e32 v52, v59, v59
	v_fmac_f32_e32 v51, v60, v60
	v_fmac_f32_e32 v52, v58, v58
	v_add_f32_e32 v51, v51, v52
	v_add_f32_e32 v50, v50, v51
	v_add_f32_e32 v50, v104, v50
	ds_bpermute_b32 v51, v191, v50
	s_waitcnt lgkmcnt(0)
	v_add_f32_e32 v50, v50, v51
	ds_bpermute_b32 v51, v190, v50
	s_and_saveexec_b64 s[60:61], vcc
	s_cbranch_execz .LBB0_77
	s_waitcnt lgkmcnt(0)
	v_add_f32_e32 v52, v50, v51
	s_lshl_b32 s22, s46, 2
	v_lshlrev_b64 v[50:51], 6, v[102:103]
	s_ashr_i32 s23, s22, 31
	v_lshl_add_u64 v[50:51], s[84:85], 0, v[50:51]
	v_lshl_add_u64 v[50:51], s[22:23], 2, v[50:51]
	s_lshl_b32 s86, s74, 2
	v_lshl_add_u64 v[50:51], v[50:51], 0, s[86:87]
	global_store_dword v[50:51], v52, off
.LBB0_77:
	s_or_b64 exec, exec, s[60:61]
	s_waitcnt vmcnt(7)
	v_lshlrev_b32_e32 v50, 16, v218
	s_waitcnt lgkmcnt(0)
	v_and_b32_e32 v51, 0xffff0000, v218
	v_lshlrev_b32_e32 v52, 16, v219
	v_and_b32_e32 v53, 0xffff0000, v219
	v_lshlrev_b32_e32 v54, 16, v220
	v_and_b32_e32 v55, 0xffff0000, v220
	v_pk_add_f32 v[46:47], v[46:47], v[50:51]
	v_pk_add_f32 v[48:49], v[48:49], v[52:53]
	v_pk_add_f32 v[52:53], v[42:43], v[54:55]
	v_cvt_pk_bf16_f32 v42, v46, v47
	v_mul_f32_e32 v47, v47, v47
	v_lshlrev_b32_e32 v56, 16, v221
	v_and_b32_e32 v57, 0xffff0000, v221
	v_fmac_f32_e32 v47, v46, v46
	v_mul_f32_e32 v46, v49, v49
	v_pk_add_f32 v[50:51], v[44:45], v[56:57]
	v_fmac_f32_e32 v46, v48, v48
	v_cvt_pk_bf16_f32 v43, v48, v49
	v_add_f32_e32 v46, v47, v46
	v_mul_f32_e32 v47, v53, v53
	v_mul_f32_e32 v48, v51, v51
	v_fmac_f32_e32 v47, v52, v52
	v_fmac_f32_e32 v48, v50, v50
	v_add_f32_e32 v47, v47, v48
	v_add_f32_e32 v54, v46, v47
	s_waitcnt vmcnt(6)
	v_lshlrev_b32_e32 v46, 16, v222
	v_and_b32_e32 v47, 0xffff0000, v222
	v_lshlrev_b32_e32 v48, 16, v223
	v_and_b32_e32 v49, 0xffff0000, v223
	v_cvt_pk_bf16_f32 v45, v50, v51
	v_lshlrev_b32_e32 v50, 16, v224
	v_and_b32_e32 v51, 0xffff0000, v224
	v_pk_add_f32 v[40:41], v[40:41], v[48:49]
	v_pk_add_f32 v[38:39], v[38:39], v[46:47]
	v_cvt_pk_bf16_f32 v44, v52, v53
	v_lshlrev_b32_e32 v52, 16, v225
	v_and_b32_e32 v53, 0xffff0000, v225
	v_pk_add_f32 v[48:49], v[34:35], v[50:51]
	v_mul_f32_e32 v34, v39, v39
	v_mul_f32_e32 v35, v41, v41
	v_pk_add_f32 v[46:47], v[36:37], v[52:53]
	v_fmac_f32_e32 v34, v38, v38
	v_fmac_f32_e32 v35, v40, v40
	v_add_f32_e32 v34, v34, v35
	v_mul_f32_e32 v35, v49, v49
	v_mul_f32_e32 v36, v47, v47
	v_fmac_f32_e32 v35, v48, v48
	v_fmac_f32_e32 v36, v46, v46
	v_add_f32_e32 v35, v35, v36
	v_add_f32_e32 v34, v34, v35
	v_add_f32_e32 v37, v54, v34
	ds_bpermute_b32 v52, v191, v37
	v_lshl_add_u64 v[34:35], s[36:37], 0, v[100:101]
	v_lshl_add_u64 v[50:51], v[168:169], 1, v[34:35]
	v_cvt_pk_bf16_f32 v36, v38, v39
	v_cvt_pk_bf16_f32 v38, v48, v49
	s_waitcnt lgkmcnt(0)
	v_add_f32_e32 v34, v37, v52
	ds_bpermute_b32 v35, v190, v34
	v_cvt_pk_bf16_f32 v37, v40, v41
	v_cvt_pk_bf16_f32 v39, v46, v47
	global_store_dwordx4 v[50:51], v[42:45], off
	global_store_dwordx4 v[50:51], v[36:39], off offset:256
	s_and_saveexec_b64 s[60:61], vcc
	s_cbranch_execz .LBB0_79
	s_waitcnt lgkmcnt(0)
	v_add_f32_e32 v36, v34, v35
	s_lshl_b32 s22, s46, 2
	v_lshlrev_b64 v[34:35], 6, v[98:99]
	s_ashr_i32 s23, s22, 31
	v_lshl_add_u64 v[34:35], s[84:85], 0, v[34:35]
	v_lshl_add_u64 v[34:35], s[22:23], 2, v[34:35]
	s_lshl_b32 s86, s74, 2
	v_lshl_add_u64 v[34:35], v[34:35], 0, s[86:87]
	global_store_dword v[34:35], v36, off
; __device__ __forceinline__ float shx(float v, int lane, int o) { return __int_as_float(__builtin_amdgcn_ds_bpermute((lane ^ o) << 2, __float_as_int(v))); }
; __device__ __forceinline__ u32x4 pack8(const f32x4 a, const f32x4 b) { u32x4 w; w.x = cvt_pk_bf16(a[0], a[1]); w.y = cvt_pk_bf16(a[2], a[3]); w.z = cvt_pk_bf16(b[0], b[1]); w.w = cvt_pk_bf16(b[2], b[3]); return w; }
; __device__ __forceinline__ void unpack8(const u32x4 w, f32x4& a, f32x4& b) { a = (f32x4){bflo(w.x), bfhi(w.x), bflo(w.y), bfhi(w.y)}; b = (f32x4){bflo(w.z), bfhi(w.z), bflo(w.w), bfhi(w.w)}; }
;     __device__ __forceinline__ void operator()(const Acc& acc, const Unit& u, int wr, int wc, int fr, int fq) const {
;     ...
;             for (int m = 0; m < 4; ++m) { const size_t row = (size_t)(row0 + ai * 128 + m * 16); float sq = 0.f;
; #pragma unroll
;                 for (int bj = 0; bj < 2; ++bj) { f32x4 o0, o1; unpack8(hv[m][bj], o0, o1); o0 += acc[ai][bj][m][0] * sc; o1 += acc[ai][bj][m][1] * sc;
;                     *(u32x4*)(hb + row * DM + col0 + bj * 128) = pack8(o0, o1);
;                     sq += ((o0[0] * o0[0] + o0[1] * o0[1]) + (o0[2] * o0[2] + o0[3] * o0[3])) + ((o1[0] * o1[0] + o1[1] * o1[1]) + (o1[2] * o1[2] + o1[3] * o1[3])); }
;                 const int lane = fq * 16 + fr; sq += shx(sq, lane, 16); sq += shx(sq, lane, 32);
;                 if (fq == 0) ssq[row * 16 + u.pn * 4 + wc] = sq; } }
.LBB0_79:
	s_or_b64 exec, exec, s[60:61]
	s_waitcnt vmcnt(7)
	v_lshlrev_b32_e32 v34, 16, v240
	s_waitcnt lgkmcnt(0)
	v_and_b32_e32 v35, 0xffff0000, v240
	v_lshlrev_b32_e32 v36, 16, v241
	v_and_b32_e32 v37, 0xffff0000, v241
	v_lshlrev_b32_e32 v38, 16, v242
	v_and_b32_e32 v39, 0xffff0000, v242
	v_pk_add_f32 v[30:31], v[30:31], v[34:35]
	v_pk_add_f32 v[32:33], v[32:33], v[36:37]
	v_pk_add_f32 v[36:37], v[26:27], v[38:39]
	v_cvt_pk_bf16_f32 v26, v30, v31
	v_mul_f32_e32 v31, v31, v31
	v_lshlrev_b32_e32 v40, 16, v243
	v_and_b32_e32 v41, 0xffff0000, v243
	v_fmac_f32_e32 v31, v30, v30
	v_mul_f32_e32 v30, v33, v33
	v_pk_add_f32 v[34:35], v[28:29], v[40:41]
	v_fmac_f32_e32 v30, v32, v32
	v_cvt_pk_bf16_f32 v27, v32, v33
	v_add_f32_e32 v30, v31, v30
	v_mul_f32_e32 v31, v37, v37
	v_mul_f32_e32 v32, v35, v35
	v_fmac_f32_e32 v31, v36, v36
	v_fmac_f32_e32 v32, v34, v34
	v_add_f32_e32 v31, v31, v32
	v_add_f32_e32 v38, v30, v31
	s_waitcnt vmcnt(6)
	v_lshlrev_b32_e32 v30, 16, v244
	v_and_b32_e32 v31, 0xffff0000, v244
	v_lshlrev_b32_e32 v32, 16, v245
	v_and_b32_e32 v33, 0xffff0000, v245
	v_cvt_pk_bf16_f32 v29, v34, v35
	v_lshlrev_b32_e32 v34, 16, v246
	v_and_b32_e32 v35, 0xffff0000, v246
	v_pk_add_f32 v[24:25], v[24:25], v[32:33]
	v_pk_add_f32 v[22:23], v[22:23], v[30:31]
	v_cvt_pk_bf16_f32 v28, v36, v37
	v_lshlrev_b32_e32 v36, 16, v247
	v_and_b32_e32 v37, 0xffff0000, v247
	v_pk_add_f32 v[32:33], v[18:19], v[34:35]
	v_mul_f32_e32 v18, v23, v23
	v_mul_f32_e32 v19, v25, v25
	v_pk_add_f32 v[30:31], v[20:21], v[36:37]
	v_fmac_f32_e32 v18, v22, v22
	v_fmac_f32_e32 v19, v24, v24
	v_add_f32_e32 v18, v18, v19
	v_mul_f32_e32 v19, v33, v33
	v_mul_f32_e32 v20, v31, v31
	v_fmac_f32_e32 v19, v32, v32
	v_fmac_f32_e32 v20, v30, v30
	v_add_f32_e32 v19, v19, v20
	v_add_f32_e32 v18, v18, v19
	v_add_f32_e32 v21, v38, v18
	ds_bpermute_b32 v36, v191, v21
	v_lshl_add_u64 v[18:19], s[36:37], 0, v[96:97]
	v_lshl_add_u64 v[34:35], v[168:169], 1, v[18:19]
	v_cvt_pk_bf16_f32 v20, v22, v23
	v_cvt_pk_bf16_f32 v22, v32, v33
	s_waitcnt lgkmcnt(0)
	v_add_f32_e32 v18, v21, v36
	ds_bpermute_b32 v19, v190, v18
	v_cvt_pk_bf16_f32 v21, v24, v25
	v_cvt_pk_bf16_f32 v23, v30, v31
	global_store_dwordx4 v[34:35], v[26:29], off
	global_store_dwordx4 v[34:35], v[20:23], off offset:256
	s_and_saveexec_b64 s[60:61], vcc
	s_cbranch_execz .LBB0_81
	s_waitcnt lgkmcnt(0)
	v_add_f32_e32 v20, v18, v19
	s_lshl_b32 s22, s46, 2
	v_lshlrev_b64 v[18:19], 6, v[94:95]
	s_ashr_i32 s23, s22, 31
	v_lshl_add_u64 v[18:19], s[84:85], 0, v[18:19]
	v_lshl_add_u64 v[18:19], s[22:23], 2, v[18:19]
	s_lshl_b32 s86, s74, 2
	v_lshl_add_u64 v[18:19], v[18:19], 0, s[86:87]
	global_store_dword v[18:19], v20, off
.LBB0_81:
	s_or_b64 exec, exec, s[60:61]
	s_waitcnt vmcnt(7)
	v_lshlrev_b32_e32 v18, 16, v248
	s_waitcnt lgkmcnt(0)
	v_and_b32_e32 v19, 0xffff0000, v248
	v_lshlrev_b32_e32 v20, 16, v249
	v_and_b32_e32 v21, 0xffff0000, v249
	v_lshlrev_b32_e32 v22, 16, v250
	v_and_b32_e32 v23, 0xffff0000, v250
	v_pk_add_f32 v[14:15], v[14:15], v[18:19]
	v_pk_add_f32 v[16:17], v[16:17], v[20:21]
	v_pk_add_f32 v[20:21], v[10:11], v[22:23]
	v_cvt_pk_bf16_f32 v10, v14, v15
	v_mul_f32_e32 v15, v15, v15
	v_lshlrev_b32_e32 v24, 16, v251
	v_and_b32_e32 v25, 0xffff0000, v251
	v_fmac_f32_e32 v15, v14, v14
	v_mul_f32_e32 v14, v17, v17
	v_pk_add_f32 v[18:19], v[12:13], v[24:25]
	v_fmac_f32_e32 v14, v16, v16
	v_cvt_pk_bf16_f32 v11, v16, v17
	v_add_f32_e32 v14, v15, v14
	v_mul_f32_e32 v15, v21, v21
	v_mul_f32_e32 v16, v19, v19
	v_fmac_f32_e32 v15, v20, v20
	v_fmac_f32_e32 v16, v18, v18
	v_add_f32_e32 v15, v15, v16
	v_add_f32_e32 v22, v14, v15
	s_waitcnt vmcnt(6)
	v_lshlrev_b32_e32 v14, 16, v226
	v_and_b32_e32 v15, 0xffff0000, v226
	v_lshlrev_b32_e32 v16, 16, v227
	v_and_b32_e32 v17, 0xffff0000, v227
	v_cvt_pk_bf16_f32 v13, v18, v19
	v_lshlrev_b32_e32 v18, 16, v239
	v_and_b32_e32 v19, 0xffff0000, v239
	v_pk_add_f32 v[8:9], v[8:9], v[16:17]
	v_pk_add_f32 v[6:7], v[6:7], v[14:15]
	v_cvt_pk_bf16_f32 v12, v20, v21
	v_lshlrev_b32_e32 v20, 16, v159
	v_and_b32_e32 v21, 0xffff0000, v159
	v_pk_add_f32 v[16:17], v[2:3], v[18:19]
	v_mul_f32_e32 v2, v7, v7
	v_mul_f32_e32 v3, v9, v9
	v_pk_add_f32 v[14:15], v[4:5], v[20:21]
	v_fmac_f32_e32 v2, v6, v6
	v_fmac_f32_e32 v3, v8, v8
	v_add_f32_e32 v2, v2, v3
	v_mul_f32_e32 v3, v17, v17
	v_mul_f32_e32 v4, v15, v15
	v_fmac_f32_e32 v3, v16, v16
	v_fmac_f32_e32 v4, v14, v14
	v_add_f32_e32 v3, v3, v4
	v_add_f32_e32 v2, v2, v3
	v_add_f32_e32 v5, v22, v2
	ds_bpermute_b32 v20, v191, v5
	v_lshl_add_u64 v[2:3], s[36:37], 0, v[92:93]
	v_lshl_add_u64 v[18:19], v[168:169], 1, v[2:3]
	v_cvt_pk_bf16_f32 v4, v6, v7
	v_cvt_pk_bf16_f32 v6, v16, v17
	s_waitcnt lgkmcnt(0)
	v_add_f32_e32 v2, v5, v20
	ds_bpermute_b32 v3, v190, v2
	v_cvt_pk_bf16_f32 v5, v8, v9
	v_cvt_pk_bf16_f32 v7, v14, v15
	global_store_dwordx4 v[18:19], v[10:13], off
	global_store_dwordx4 v[18:19], v[4:7], off offset:256
	s_and_saveexec_b64 s[60:61], vcc
	s_cbranch_execz .LBB0_46
	s_waitcnt lgkmcnt(0)
	v_add_f32_e32 v4, v2, v3
	s_lshl_b32 s22, s46, 2
	v_lshlrev_b64 v[2:3], 6, v[90:91]
	s_ashr_i32 s23, s22, 31
	v_lshl_add_u64 v[2:3], s[84:85], 0, v[2:3]
	v_lshl_add_u64 v[2:3], s[22:23], 2, v[2:3]
	s_lshl_b32 s86, s74, 2
	v_lshl_add_u64 v[2:3], v[2:3], 0, s[86:87]
	global_store_dword v[2:3], v4, off
	s_branch .LBB0_46

; __device__ __forceinline__ float shx(float v, int lane, int o) { return __int_as_float(__builtin_amdgcn_ds_bpermute((lane ^ o) << 2, __float_as_int(v))); }
; __device__ __forceinline__ u32x4 pack8(const f32x4 a, const f32x4 b) { u32x4 w; w.x = cvt_pk_bf16(a[0], a[1]); w.y = cvt_pk_bf16(a[2], a[3]); w.z = cvt_pk_bf16(b[0], b[1]); w.w = cvt_pk_bf16(b[2], b[3]); return w; }
; __device__ __forceinline__ void unpack8(const u32x4 w, f32x4& a, f32x4& b) { a = (f32x4){bflo(w.x), bfhi(w.x), bflo(w.y), bfhi(w.y)}; b = (f32x4){bflo(w.z), bfhi(w.z), bflo(w.w), bfhi(w.w)}; }
;     __device__ __forceinline__ void operator()(const Acc& acc, const Unit& u, int wr, int wc, int fr, int fq) const {
;     ...
;         for (int ai = 0; ai < 2; ++ai) {
;             u32x4 hv[4][2];
; #pragma unroll
;             for (int m = 0; m < 4; ++m)
; #pragma unroll
;                 for (int bj = 0; bj < 2; ++bj) hv[m][bj] = *(const u32x4*)(hb + (size_t)(row0 + ai * 128 + m * 16) * DM + col0 + bj * 128);
; #pragma unroll
;             for (int m = 0; m < 4; ++m) { const size_t row = (size_t)(row0 + ai * 128 + m * 16); float sq = 0.f;
; #pragma unroll
;                 for (int bj = 0; bj < 2; ++bj) { f32x4 o0, o1; unpack8(hv[m][bj], o0, o1); o0 += acc[ai][bj][m][0] * sc; o1 += acc[ai][bj][m][1] * sc;
;                     *(u32x4*)(hb + row * DM + col0 + bj * 128) = pack8(o0, o1);
;                     sq += ((o0[0] * o0[0] + o0[1] * o0[1]) + (o0[2] * o0[2] + o0[3] * o0[3])) + ((o1[0] * o1[0] + o1[1] * o1[1]) + (o1[2] * o1[2] + o1[3] * o1[3])); }
;                 const int lane = fq * 16 + fr; sq += shx(sq, lane, 16); sq += shx(sq, lane, 32);
;                 if (fq == 0) ssq[row * 16 + u.pn * 4 + wc] = sq; } }
.LBB0_213:
	v_readlane_b32 s92, v253, 42
	s_andn2_b64 vcc, exec, s[66:67]
	s_cbranch_vccnz .LBB0_197
	v_lshl_add_u32 v172, s64, 8, v130
	v_lshlrev_b32_e32 v130, 2, v133
	v_lshlrev_b64 v[202:203], 1, v[168:169]
	v_ashrrev_i32_e32 v173, 31, v172
	v_lshl_add_u32 v130, v132, 6, v130
	v_lshl_add_u64 v[170:171], s[36:37], 0, v[202:203]
	v_lshlrev_b64 v[204:205], 11, v[172:173]
	v_xor_b32_e32 v191, 64, v130
	v_xor_b32_e32 v190, 0x80, v130
	v_lshl_add_u64 v[130:131], v[170:171], 0, v[204:205]
	s_mov_b32 s100, 0x40000
	s_mov_b32 s101, 0
	global_load_dwordx4 v[192:195], v[130:131], off
	global_load_dwordx4 v[154:157], v[130:131], off offset:256
	v_lshl_add_u64 v[206:207], v[130:131], 0, s[100:101]
	global_load_dwordx4 v[210:213], v[206:207], off
	global_load_dwordx4 v[214:217], v[206:207], off offset:256
	v_add_u32_e32 v182, 16, v172
	v_ashrrev_i32_e32 v183, 31, v182
	v_add_u32_e32 v178, 32, v172
	v_lshlrev_b64 v[184:185], 11, v[182:183]
	v_ashrrev_i32_e32 v179, 31, v178
	v_add_u32_e32 v174, 48, v172
	v_lshl_add_u64 v[130:131], v[170:171], 0, v[184:185]
	v_lshlrev_b64 v[180:181], 11, v[178:179]
	v_ashrrev_i32_e32 v175, 31, v174
	global_load_dwordx4 v[150:153], v[130:131], off
	global_load_dwordx4 v[146:149], v[130:131], off offset:256
	v_lshl_add_u64 v[206:207], v[130:131], 0, s[100:101]
	global_load_dwordx4 v[218:221], v[206:207], off
	global_load_dwordx4 v[222:225], v[206:207], off offset:256
	v_lshl_add_u64 v[130:131], v[170:171], 0, v[180:181]
	v_lshlrev_b64 v[176:177], 11, v[174:175]
	global_load_dwordx4 v[142:145], v[130:131], off
	global_load_dwordx4 v[138:141], v[130:131], off offset:256
	v_lshl_add_u64 v[206:207], v[130:131], 0, s[100:101]
	global_load_dwordx4 v[240:243], v[206:207], off
	global_load_dwordx4 v[244:247], v[206:207], off offset:256
	v_lshl_add_u64 v[130:131], v[170:171], 0, v[176:177]
	v_cmp_eq_u32_e32 vcc, 0, v132
	v_lshl_add_u64 v[206:207], v[130:131], 0, s[100:101]
	global_load_dwordx4 v[248:251], v[206:207], off
	global_load_dwordx2 v[226:227], v[206:207], off offset:256
	global_load_dword v239, v[206:207], off offset:264
	global_load_dword v159, v[206:207], off offset:268
	global_load_dwordx4 v[134:137], v[130:131], off
	s_nop 0
	global_load_dwordx4 v[130:133], v[130:131], off offset:256
	v_lshl_add_u64 v[204:205], s[36:37], 0, v[204:205]
	v_lshl_add_u64 v[202:203], v[204:205], 0, v[202:203]
	s_waitcnt vmcnt(0)
	v_lshlrev_b32_e32 v206, 16, v192
	v_and_b32_e32 v207, 0xffff0000, v192
	v_lshlrev_b32_e32 v192, 16, v193
	v_and_b32_e32 v193, 0xffff0000, v193
	v_lshlrev_b32_e32 v208, 16, v194
	v_and_b32_e32 v209, 0xffff0000, v194
	v_lshlrev_b32_e32 v194, 16, v195
	v_and_b32_e32 v195, 0xffff0000, v195
	v_pk_add_f32 v[128:129], v[128:129], v[192:193]
	v_pk_add_f32 v[126:127], v[126:127], v[206:207]
	v_pk_add_f32 v[192:193], v[124:125], v[194:195]
	v_pk_add_f32 v[194:195], v[122:123], v[208:209]
	v_cvt_pk_bf16_f32 v122, v126, v127
	v_cvt_pk_bf16_f32 v123, v128, v129
	v_cvt_pk_bf16_f32 v124, v194, v195
	v_cvt_pk_bf16_f32 v125, v192, v193
	global_store_dwordx4 v[202:203], v[122:125], off
	s_nop 1
	v_mul_f32_e32 v122, v127, v127
	v_mul_f32_e32 v123, v129, v129
	v_fmac_f32_e32 v122, v126, v126
	v_fmac_f32_e32 v123, v128, v128
	v_add_f32_e32 v122, v122, v123
	v_mul_f32_e32 v123, v195, v195
	v_mul_f32_e32 v124, v193, v193
	v_fmac_f32_e32 v123, v194, v194
	v_fmac_f32_e32 v124, v192, v192
	v_add_f32_e32 v123, v123, v124
	v_add_f32_e32 v192, v122, v123
	v_lshlrev_b32_e32 v122, 16, v154
	v_and_b32_e32 v123, 0xffff0000, v154
	v_lshlrev_b32_e32 v124, 16, v155
	v_and_b32_e32 v125, 0xffff0000, v155
	v_lshlrev_b32_e32 v126, 16, v156
	v_and_b32_e32 v127, 0xffff0000, v156
	v_lshlrev_b32_e32 v128, 16, v157
	v_and_b32_e32 v129, 0xffff0000, v157
	v_pk_add_f32 v[120:121], v[120:121], v[124:125]
	v_pk_add_f32 v[118:119], v[118:119], v[122:123]
	v_pk_add_f32 v[122:123], v[116:117], v[128:129]
	v_pk_add_f32 v[124:125], v[114:115], v[126:127]
	v_cvt_pk_bf16_f32 v114, v118, v119
	v_cvt_pk_bf16_f32 v115, v120, v121
	v_cvt_pk_bf16_f32 v116, v124, v125
	v_cvt_pk_bf16_f32 v117, v122, v123
	global_store_dwordx4 v[202:203], v[114:117], off offset:256
	s_nop 1
	v_mul_f32_e32 v114, v119, v119
	v_mul_f32_e32 v115, v121, v121
	v_fmac_f32_e32 v114, v118, v118
	v_fmac_f32_e32 v115, v120, v120
	v_add_f32_e32 v114, v114, v115
	v_mul_f32_e32 v115, v125, v125
	v_mul_f32_e32 v116, v123, v123
	v_fmac_f32_e32 v115, v124, v124
	v_fmac_f32_e32 v116, v122, v122
	v_add_f32_e32 v115, v115, v116
	v_add_f32_e32 v114, v114, v115
	v_add_f32_e32 v114, v192, v114
	ds_bpermute_b32 v115, v191, v114
	s_waitcnt lgkmcnt(0)
	v_add_f32_e32 v114, v114, v115
	ds_bpermute_b32 v115, v190, v114
	s_and_saveexec_b64 s[64:65], vcc
	s_cbranch_execz .LBB0_216
	s_waitcnt lgkmcnt(0)
	v_add_f32_e32 v116, v114, v115
	s_lshl_b32 s66, s42, 2
	v_lshlrev_b64 v[114:115], 6, v[172:173]
	s_ashr_i32 s67, s66, 31
	v_lshl_add_u64 v[114:115], s[4:5], 0, v[114:115]
	v_lshl_add_u64 v[114:115], s[66:67], 2, v[114:115]
	s_lshl_b32 s86, s29, 2
	v_lshl_add_u64 v[114:115], v[114:115], 0, s[86:87]
	global_store_dword v[114:115], v116, off

; __device__ __forceinline__ float shx(float v, int lane, int o) { return __int_as_float(__builtin_amdgcn_ds_bpermute((lane ^ o) << 2, __float_as_int(v))); }
; __device__ __forceinline__ u32x4 pack8(const f32x4 a, const f32x4 b) { u32x4 w; w.x = cvt_pk_bf16(a[0], a[1]); w.y = cvt_pk_bf16(a[2], a[3]); w.z = cvt_pk_bf16(b[0], b[1]); w.w = cvt_pk_bf16(b[2], b[3]); return w; }
; __device__ __forceinline__ void unpack8(const u32x4 w, f32x4& a, f32x4& b) { a = (f32x4){bflo(w.x), bfhi(w.x), bflo(w.y), bfhi(w.y)}; b = (f32x4){bflo(w.z), bfhi(w.z), bflo(w.w), bfhi(w.w)}; }
;     __device__ __forceinline__ void operator()(const Acc& acc, const Unit& u, int wr, int wc, int fr, int fq) const {
;     ...
;             for (int m = 0; m < 4; ++m)
; #pragma unroll
;                 for (int bj = 0; bj < 2; ++bj) hv[m][bj] = *(const u32x4*)(hb + (size_t)(row0 + ai * 128 + m * 16) * DM + col0 + bj * 128);
; #pragma unroll
;             for (int m = 0; m < 4; ++m) { const size_t row = (size_t)(row0 + ai * 128 + m * 16); float sq = 0.f;
; #pragma unroll
;                 for (int bj = 0; bj < 2; ++bj) { f32x4 o0, o1; unpack8(hv[m][bj], o0, o1); o0 += acc[ai][bj][m][0] * sc; o1 += acc[ai][bj][m][1] * sc;
;                     *(u32x4*)(hb + row * DM + col0 + bj * 128) = pack8(o0, o1);
;                     sq += ((o0[0] * o0[0] + o0[1] * o0[1]) + (o0[2] * o0[2] + o0[3] * o0[3])) + ((o1[0] * o1[0] + o1[1] * o1[1]) + (o1[2] * o1[2] + o1[3] * o1[3])); }
;                 const int lane = fq * 16 + fr; sq += shx(sq, lane, 16); sq += shx(sq, lane, 32);
;                 if (fq == 0) ssq[row * 16 + u.pn * 4 + wc] = sq; } }
.LBB0_222:
	s_or_b64 exec, exec, s[64:65]
	v_add_u32_e32 v102, 0x80, v172
	v_ashrrev_i32_e32 v103, 31, v102
	v_lshlrev_b64 v[112:113], 11, v[102:103]
	s_waitcnt lgkmcnt(0)
	v_lshl_add_u64 v[66:67], v[170:171], 0, v[112:113]
	v_add_u32_e32 v98, 0x90, v172
	v_ashrrev_i32_e32 v99, 31, v98
	v_add_u32_e32 v94, 0xa0, v172
	v_lshlrev_b64 v[100:101], 11, v[98:99]
	v_ashrrev_i32_e32 v95, 31, v94
	v_add_u32_e32 v90, 0xb0, v172
	v_lshl_add_u64 v[66:67], v[170:171], 0, v[100:101]
	v_lshlrev_b64 v[96:97], 11, v[94:95]
	v_ashrrev_i32_e32 v91, 31, v90
	v_lshl_add_u64 v[66:67], v[170:171], 0, v[96:97]
	v_lshlrev_b64 v[92:93], 11, v[90:91]
	v_lshl_add_u64 v[66:67], v[170:171], 0, v[92:93]
	s_nop 0
	v_lshl_add_u64 v[112:113], s[36:37], 0, v[112:113]
	v_lshl_add_u64 v[112:113], v[168:169], 1, v[112:113]
	s_waitcnt vmcnt(7)
	v_lshlrev_b32_e32 v114, 16, v210
	v_and_b32_e32 v115, 0xffff0000, v210
	v_lshlrev_b32_e32 v104, 16, v211
	v_and_b32_e32 v105, 0xffff0000, v211
	v_lshlrev_b32_e32 v116, 16, v212
	v_and_b32_e32 v117, 0xffff0000, v212
	v_lshlrev_b32_e32 v106, 16, v213
	v_and_b32_e32 v107, 0xffff0000, v213
	v_pk_add_f32 v[64:65], v[64:65], v[104:105]
	v_pk_add_f32 v[62:63], v[62:63], v[114:115]
	v_pk_add_f32 v[104:105], v[60:61], v[106:107]
	v_pk_add_f32 v[106:107], v[58:59], v[116:117]
	v_cvt_pk_bf16_f32 v58, v62, v63
	v_cvt_pk_bf16_f32 v59, v64, v65
	v_cvt_pk_bf16_f32 v60, v106, v107
	v_cvt_pk_bf16_f32 v61, v104, v105
	global_store_dwordx4 v[112:113], v[58:61], off
	s_nop 1
	v_mul_f32_e32 v58, v63, v63
	v_mul_f32_e32 v59, v65, v65
	v_fmac_f32_e32 v58, v62, v62
	v_fmac_f32_e32 v59, v64, v64
	v_add_f32_e32 v58, v58, v59
	v_mul_f32_e32 v59, v107, v107
	v_mul_f32_e32 v60, v105, v105
	v_fmac_f32_e32 v59, v106, v106
	v_fmac_f32_e32 v60, v104, v104
	v_add_f32_e32 v59, v59, v60
	v_add_f32_e32 v104, v58, v59
	s_waitcnt vmcnt(7)
	v_lshlrev_b32_e32 v58, 16, v214
	v_and_b32_e32 v59, 0xffff0000, v214
	v_lshlrev_b32_e32 v60, 16, v215
	v_and_b32_e32 v61, 0xffff0000, v215
	v_lshlrev_b32_e32 v62, 16, v216
	v_and_b32_e32 v63, 0xffff0000, v216
	v_lshlrev_b32_e32 v64, 16, v217
	v_and_b32_e32 v65, 0xffff0000, v217
	v_pk_add_f32 v[56:57], v[56:57], v[60:61]
	v_pk_add_f32 v[54:55], v[54:55], v[58:59]
	v_pk_add_f32 v[58:59], v[52:53], v[64:65]
	v_pk_add_f32 v[60:61], v[50:51], v[62:63]
	v_cvt_pk_bf16_f32 v50, v54, v55
	v_cvt_pk_bf16_f32 v51, v56, v57
	v_cvt_pk_bf16_f32 v52, v60, v61
	v_cvt_pk_bf16_f32 v53, v58, v59
	global_store_dwordx4 v[112:113], v[50:53], off offset:256
	s_nop 1
	v_mul_f32_e32 v50, v55, v55
	v_mul_f32_e32 v51, v57, v57
	v_fmac_f32_e32 v50, v54, v54
	v_fmac_f32_e32 v51, v56, v56
	v_add_f32_e32 v50, v50, v51
	v_mul_f32_e32 v51, v61, v61
	v_mul_f32_e32 v52, v59, v59
	v_fmac_f32_e32 v51, v60, v60
	v_fmac_f32_e32 v52, v58, v58
	v_add_f32_e32 v51, v51, v52
	v_add_f32_e32 v50, v50, v51
	v_add_f32_e32 v50, v104, v50
	ds_bpermute_b32 v51, v191, v50
	s_waitcnt lgkmcnt(0)
	v_add_f32_e32 v50, v50, v51
	ds_bpermute_b32 v51, v190, v50
	s_and_saveexec_b64 s[64:65], vcc
	s_cbranch_execz .LBB0_224
	s_waitcnt lgkmcnt(0)
	v_add_f32_e32 v52, v50, v51
	s_lshl_b32 s66, s42, 2
	v_lshlrev_b64 v[50:51], 6, v[102:103]
	s_ashr_i32 s67, s66, 31
	v_lshl_add_u64 v[50:51], s[4:5], 0, v[50:51]
	v_lshl_add_u64 v[50:51], s[66:67], 2, v[50:51]
	s_lshl_b32 s86, s29, 2
	v_lshl_add_u64 v[50:51], v[50:51], 0, s[86:87]
	global_store_dword v[50:51], v52, off
.LBB0_224:
	s_or_b64 exec, exec, s[64:65]
	s_waitcnt vmcnt(7)
	v_lshlrev_b32_e32 v50, 16, v218
	s_waitcnt lgkmcnt(0)
	v_and_b32_e32 v51, 0xffff0000, v218
	v_lshlrev_b32_e32 v52, 16, v219
	v_and_b32_e32 v53, 0xffff0000, v219
	v_lshlrev_b32_e32 v54, 16, v220
	v_and_b32_e32 v55, 0xffff0000, v220
	v_pk_add_f32 v[46:47], v[46:47], v[50:51]
	v_pk_add_f32 v[48:49], v[48:49], v[52:53]
	v_pk_add_f32 v[52:53], v[42:43], v[54:55]
	v_cvt_pk_bf16_f32 v42, v46, v47
	v_mul_f32_e32 v47, v47, v47
	v_lshlrev_b32_e32 v56, 16, v221
	v_and_b32_e32 v57, 0xffff0000, v221
	v_fmac_f32_e32 v47, v46, v46
	v_mul_f32_e32 v46, v49, v49
	v_pk_add_f32 v[50:51], v[44:45], v[56:57]
	v_fmac_f32_e32 v46, v48, v48
	v_cvt_pk_bf16_f32 v43, v48, v49
	v_add_f32_e32 v46, v47, v46
	v_mul_f32_e32 v47, v53, v53
	v_mul_f32_e32 v48, v51, v51
	v_fmac_f32_e32 v47, v52, v52
	v_fmac_f32_e32 v48, v50, v50
	v_add_f32_e32 v47, v47, v48
	v_add_f32_e32 v54, v46, v47
	s_waitcnt vmcnt(6)
	v_lshlrev_b32_e32 v46, 16, v222
	v_and_b32_e32 v47, 0xffff0000, v222
	v_lshlrev_b32_e32 v48, 16, v223
	v_and_b32_e32 v49, 0xffff0000, v223
	v_cvt_pk_bf16_f32 v45, v50, v51
	v_lshlrev_b32_e32 v50, 16, v224
	v_and_b32_e32 v51, 0xffff0000, v224
	v_pk_add_f32 v[40:41], v[40:41], v[48:49]
	v_pk_add_f32 v[38:39], v[38:39], v[46:47]
	v_cvt_pk_bf16_f32 v44, v52, v53
	v_lshlrev_b32_e32 v52, 16, v225
	v_and_b32_e32 v53, 0xffff0000, v225
	v_pk_add_f32 v[48:49], v[34:35], v[50:51]
	v_mul_f32_e32 v34, v39, v39
	v_mul_f32_e32 v35, v41, v41
	v_pk_add_f32 v[46:47], v[36:37], v[52:53]
	v_fmac_f32_e32 v34, v38, v38
	v_fmac_f32_e32 v35, v40, v40
	v_add_f32_e32 v34, v34, v35
	v_mul_f32_e32 v35, v49, v49
	v_mul_f32_e32 v36, v47, v47
	v_fmac_f32_e32 v35, v48, v48
	v_fmac_f32_e32 v36, v46, v46
	v_add_f32_e32 v35, v35, v36
	v_add_f32_e32 v34, v34, v35
	v_add_f32_e32 v37, v54, v34
	ds_bpermute_b32 v52, v191, v37
	v_lshl_add_u64 v[34:35], s[36:37], 0, v[100:101]
	v_lshl_add_u64 v[50:51], v[168:169], 1, v[34:35]
	v_cvt_pk_bf16_f32 v36, v38, v39
	v_cvt_pk_bf16_f32 v38, v48, v49
	s_waitcnt lgkmcnt(0)
	v_add_f32_e32 v34, v37, v52
	ds_bpermute_b32 v35, v190, v34
	v_cvt_pk_bf16_f32 v37, v40, v41
	v_cvt_pk_bf16_f32 v39, v46, v47
	global_store_dwordx4 v[50:51], v[42:45], off
	global_store_dwordx4 v[50:51], v[36:39], off offset:256
	s_and_saveexec_b64 s[64:65], vcc
	s_cbranch_execz .LBB0_226
	s_waitcnt lgkmcnt(0)
	v_add_f32_e32 v36, v34, v35
	s_lshl_b32 s66, s42, 2
	v_lshlrev_b64 v[34:35], 6, v[98:99]
	s_ashr_i32 s67, s66, 31
	v_lshl_add_u64 v[34:35], s[4:5], 0, v[34:35]
	v_lshl_add_u64 v[34:35], s[66:67], 2, v[34:35]
	s_lshl_b32 s86, s29, 2
	v_lshl_add_u64 v[34:35], v[34:35], 0, s[86:87]
	global_store_dword v[34:35], v36, off
; __device__ __forceinline__ float shx(float v, int lane, int o) { return __int_as_float(__builtin_amdgcn_ds_bpermute((lane ^ o) << 2, __float_as_int(v))); }
; __device__ __forceinline__ u32x4 pack8(const f32x4 a, const f32x4 b) { u32x4 w; w.x = cvt_pk_bf16(a[0], a[1]); w.y = cvt_pk_bf16(a[2], a[3]); w.z = cvt_pk_bf16(b[0], b[1]); w.w = cvt_pk_bf16(b[2], b[3]); return w; }
; __device__ __forceinline__ void unpack8(const u32x4 w, f32x4& a, f32x4& b) { a = (f32x4){bflo(w.x), bfhi(w.x), bflo(w.y), bfhi(w.y)}; b = (f32x4){bflo(w.z), bfhi(w.z), bflo(w.w), bfhi(w.w)}; }
;     __device__ __forceinline__ void operator()(const Acc& acc, const Unit& u, int wr, int wc, int fr, int fq) const {
;     ...
;             for (int m = 0; m < 4; ++m) { const size_t row = (size_t)(row0 + ai * 128 + m * 16); float sq = 0.f;
; #pragma unroll
;                 for (int bj = 0; bj < 2; ++bj) { f32x4 o0, o1; unpack8(hv[m][bj], o0, o1); o0 += acc[ai][bj][m][0] * sc; o1 += acc[ai][bj][m][1] * sc;
;                     *(u32x4*)(hb + row * DM + col0 + bj * 128) = pack8(o0, o1);
;                     sq += ((o0[0] * o0[0] + o0[1] * o0[1]) + (o0[2] * o0[2] + o0[3] * o0[3])) + ((o1[0] * o1[0] + o1[1] * o1[1]) + (o1[2] * o1[2] + o1[3] * o1[3])); }
;                 const int lane = fq * 16 + fr; sq += shx(sq, lane, 16); sq += shx(sq, lane, 32);
;                 if (fq == 0) ssq[row * 16 + u.pn * 4 + wc] = sq; } }
.LBB0_226:
	s_or_b64 exec, exec, s[64:65]
	s_waitcnt vmcnt(7)
	v_lshlrev_b32_e32 v34, 16, v240
	s_waitcnt lgkmcnt(0)
	v_and_b32_e32 v35, 0xffff0000, v240
	v_lshlrev_b32_e32 v36, 16, v241
	v_and_b32_e32 v37, 0xffff0000, v241
	v_lshlrev_b32_e32 v38, 16, v242
	v_and_b32_e32 v39, 0xffff0000, v242
	v_pk_add_f32 v[30:31], v[30:31], v[34:35]
	v_pk_add_f32 v[32:33], v[32:33], v[36:37]
	v_pk_add_f32 v[36:37], v[26:27], v[38:39]
	v_cvt_pk_bf16_f32 v26, v30, v31
	v_mul_f32_e32 v31, v31, v31
	v_lshlrev_b32_e32 v40, 16, v243
	v_and_b32_e32 v41, 0xffff0000, v243
	v_fmac_f32_e32 v31, v30, v30
	v_mul_f32_e32 v30, v33, v33
	v_pk_add_f32 v[34:35], v[28:29], v[40:41]
	v_fmac_f32_e32 v30, v32, v32
	v_cvt_pk_bf16_f32 v27, v32, v33
	v_add_f32_e32 v30, v31, v30
	v_mul_f32_e32 v31, v37, v37
	v_mul_f32_e32 v32, v35, v35
	v_fmac_f32_e32 v31, v36, v36
	v_fmac_f32_e32 v32, v34, v34
	v_add_f32_e32 v31, v31, v32
	v_add_f32_e32 v38, v30, v31
	s_waitcnt vmcnt(6)
	v_lshlrev_b32_e32 v30, 16, v244
	v_and_b32_e32 v31, 0xffff0000, v244
	v_lshlrev_b32_e32 v32, 16, v245
	v_and_b32_e32 v33, 0xffff0000, v245
	v_cvt_pk_bf16_f32 v29, v34, v35
	v_lshlrev_b32_e32 v34, 16, v246
	v_and_b32_e32 v35, 0xffff0000, v246
	v_pk_add_f32 v[24:25], v[24:25], v[32:33]
	v_pk_add_f32 v[22:23], v[22:23], v[30:31]
	v_cvt_pk_bf16_f32 v28, v36, v37
	v_lshlrev_b32_e32 v36, 16, v247
	v_and_b32_e32 v37, 0xffff0000, v247
	v_pk_add_f32 v[32:33], v[18:19], v[34:35]
	v_mul_f32_e32 v18, v23, v23
	v_mul_f32_e32 v19, v25, v25
	v_pk_add_f32 v[30:31], v[20:21], v[36:37]
	v_fmac_f32_e32 v18, v22, v22
	v_fmac_f32_e32 v19, v24, v24
	v_add_f32_e32 v18, v18, v19
	v_mul_f32_e32 v19, v33, v33
	v_mul_f32_e32 v20, v31, v31
	v_fmac_f32_e32 v19, v32, v32
	v_fmac_f32_e32 v20, v30, v30
	v_add_f32_e32 v19, v19, v20
	v_add_f32_e32 v18, v18, v19
	v_add_f32_e32 v21, v38, v18
	ds_bpermute_b32 v36, v191, v21
	v_lshl_add_u64 v[18:19], s[36:37], 0, v[96:97]
	v_lshl_add_u64 v[34:35], v[168:169], 1, v[18:19]
	v_cvt_pk_bf16_f32 v20, v22, v23
	v_cvt_pk_bf16_f32 v22, v32, v33
	s_waitcnt lgkmcnt(0)
	v_add_f32_e32 v18, v21, v36
	ds_bpermute_b32 v19, v190, v18
	v_cvt_pk_bf16_f32 v21, v24, v25
	v_cvt_pk_bf16_f32 v23, v30, v31
	global_store_dwordx4 v[34:35], v[26:29], off
	global_store_dwordx4 v[34:35], v[20:23], off offset:256
	s_and_saveexec_b64 s[64:65], vcc
	s_cbranch_execz .LBB0_228
	s_waitcnt lgkmcnt(0)
	v_add_f32_e32 v20, v18, v19
	s_lshl_b32 s66, s42, 2
	v_lshlrev_b64 v[18:19], 6, v[94:95]
	s_ashr_i32 s67, s66, 31
	v_lshl_add_u64 v[18:19], s[4:5], 0, v[18:19]
	v_lshl_add_u64 v[18:19], s[66:67], 2, v[18:19]
	s_lshl_b32 s86, s29, 2
	v_lshl_add_u64 v[18:19], v[18:19], 0, s[86:87]
	global_store_dword v[18:19], v20, off
.LBB0_228:
	s_or_b64 exec, exec, s[64:65]
	s_waitcnt vmcnt(7)
	v_lshlrev_b32_e32 v18, 16, v248
	s_waitcnt lgkmcnt(0)
	v_and_b32_e32 v19, 0xffff0000, v248
	v_lshlrev_b32_e32 v20, 16, v249
	v_and_b32_e32 v21, 0xffff0000, v249
	v_lshlrev_b32_e32 v22, 16, v250
	v_and_b32_e32 v23, 0xffff0000, v250
	v_pk_add_f32 v[14:15], v[14:15], v[18:19]
	v_pk_add_f32 v[16:17], v[16:17], v[20:21]
	v_pk_add_f32 v[20:21], v[10:11], v[22:23]
	v_cvt_pk_bf16_f32 v10, v14, v15
	v_mul_f32_e32 v15, v15, v15
	v_lshlrev_b32_e32 v24, 16, v251
	v_and_b32_e32 v25, 0xffff0000, v251
	v_fmac_f32_e32 v15, v14, v14
	v_mul_f32_e32 v14, v17, v17
	v_pk_add_f32 v[18:19], v[12:13], v[24:25]
	v_fmac_f32_e32 v14, v16, v16
	v_cvt_pk_bf16_f32 v11, v16, v17
	v_add_f32_e32 v14, v15, v14
	v_mul_f32_e32 v15, v21, v21
	v_mul_f32_e32 v16, v19, v19
	v_fmac_f32_e32 v15, v20, v20
	v_fmac_f32_e32 v16, v18, v18
	v_add_f32_e32 v15, v15, v16
	v_add_f32_e32 v22, v14, v15
	s_waitcnt vmcnt(6)
	v_lshlrev_b32_e32 v14, 16, v226
	v_and_b32_e32 v15, 0xffff0000, v226
	v_lshlrev_b32_e32 v16, 16, v227
	v_and_b32_e32 v17, 0xffff0000, v227
	v_cvt_pk_bf16_f32 v13, v18, v19
	v_lshlrev_b32_e32 v18, 16, v239
	v_and_b32_e32 v19, 0xffff0000, v239
	v_pk_add_f32 v[8:9], v[8:9], v[16:17]
	v_pk_add_f32 v[6:7], v[6:7], v[14:15]
	v_cvt_pk_bf16_f32 v12, v20, v21
	v_lshlrev_b32_e32 v20, 16, v159
	v_and_b32_e32 v21, 0xffff0000, v159
	v_pk_add_f32 v[16:17], v[2:3], v[18:19]
	v_mul_f32_e32 v2, v7, v7
	v_mul_f32_e32 v3, v9, v9
	v_pk_add_f32 v[14:15], v[4:5], v[20:21]
	v_fmac_f32_e32 v2, v6, v6
	v_fmac_f32_e32 v3, v8, v8
	v_add_f32_e32 v2, v2, v3
	v_mul_f32_e32 v3, v17, v17
	v_mul_f32_e32 v4, v15, v15
	v_fmac_f32_e32 v3, v16, v16
	v_fmac_f32_e32 v4, v14, v14
	v_add_f32_e32 v3, v3, v4
	v_add_f32_e32 v2, v2, v3
	v_add_f32_e32 v5, v22, v2
	ds_bpermute_b32 v20, v191, v5
	v_lshl_add_u64 v[2:3], s[36:37], 0, v[92:93]
	v_lshl_add_u64 v[18:19], v[168:169], 1, v[2:3]
	v_cvt_pk_bf16_f32 v4, v6, v7
	v_cvt_pk_bf16_f32 v6, v16, v17
	s_waitcnt lgkmcnt(0)
	v_add_f32_e32 v2, v5, v20
	ds_bpermute_b32 v3, v190, v2
	v_cvt_pk_bf16_f32 v5, v8, v9
	v_cvt_pk_bf16_f32 v7, v14, v15
	global_store_dwordx4 v[18:19], v[10:13], off
	global_store_dwordx4 v[18:19], v[4:7], off offset:256
	s_and_saveexec_b64 s[64:65], vcc
	s_cbranch_execz .LBB0_196
	s_waitcnt lgkmcnt(0)
	v_add_f32_e32 v4, v2, v3
	s_lshl_b32 s66, s42, 2
	v_lshlrev_b64 v[2:3], 6, v[90:91]
	s_ashr_i32 s67, s66, 31
	v_lshl_add_u64 v[2:3], s[4:5], 0, v[2:3]
	v_lshl_add_u64 v[2:3], s[66:67], 2, v[2:3]
	s_lshl_b32 s86, s29, 2
	v_lshl_add_u64 v[2:3], v[2:3], 0, s[86:87]
	global_store_dword v[2:3], v4, off
	s_branch .LBB0_196
